# mLSTM conv4+SiLU rewritten with v_fmac (y += w*x per tap) instead of SLP-packed pk_mul + adds; one per-lane k scale
# speedup vs baseline: 1.0029x; 1.0029x over previous
.LBB0_385:
	s_andn2_b64 vcc, exec, s[24:25]
	s_cbranch_vccnz .LBB0_358
	ds_read_b128 v[60:63], v145
	ds_read_b128 v[44:47], v155
	ds_read_b128 v[48:51], v155 offset:16
	ds_read_b128 v[40:43], v156
	ds_read_b128 v[32:35], v156 offset:16
	ds_read_b128 v[100:103], v145 offset:8192
	ds_read_b128 v[36:39], v155 offset:512
	ds_read_b128 v[10:13], v155 offset:528
	ds_read_b128 v[52:55], v156
	ds_read_b128 v[56:59], v156 offset:16
	ds_read_b64 v[14:15], v145 offset:16384
	ds_read_b64 v[104:105], v145 offset:16392
	ds_read_b128 v[92:95], v155 offset:1024
	ds_read_b128 v[96:99], v155 offset:1040
	ds_read_b128 v[6:9], v155 offset:1536
	ds_read_b128 v[2:5], v155 offset:1552
	v_mov_b32_e32 v106, 0x3e000000
	v_cndmask_b32_e64 v106, v106, 1.0, s[6:7]
	s_waitcnt lgkmcnt(11)
	v_lshlrev_b32_e32 v0, 16, v60
	v_fmac_f32_e32 v40, v44, v0
	v_and_b32_e32 v0, 0xffff0000, v60
	v_fmac_f32_e32 v41, v45, v0
	v_lshlrev_b32_e32 v0, 16, v61
	v_fmac_f32_e32 v42, v46, v0
	v_and_b32_e32 v0, 0xffff0000, v61
	v_fmac_f32_e32 v43, v47, v0
	v_lshlrev_b32_e32 v0, 16, v62
	v_fmac_f32_e32 v32, v48, v0
	v_and_b32_e32 v0, 0xffff0000, v62
	v_fmac_f32_e32 v33, v49, v0
	v_lshlrev_b32_e32 v0, 16, v63
	v_fmac_f32_e32 v34, v50, v0
	v_and_b32_e32 v0, 0xffff0000, v63
	v_fmac_f32_e32 v35, v51, v0
	ds_read_b128 v[60:63], v145 offset:24576
	s_waitcnt lgkmcnt(7)
	v_lshlrev_b32_e32 v0, 16, v100
	v_fmac_f32_e32 v40, v36, v0
	v_fmac_f32_e32 v52, v44, v0
	v_and_b32_e32 v0, 0xffff0000, v100
	v_fmac_f32_e32 v41, v37, v0
	v_fmac_f32_e32 v53, v45, v0
	v_lshlrev_b32_e32 v0, 16, v101
	v_fmac_f32_e32 v42, v38, v0
	v_fmac_f32_e32 v54, v46, v0
	v_and_b32_e32 v0, 0xffff0000, v101
	v_fmac_f32_e32 v43, v39, v0
	v_fmac_f32_e32 v55, v47, v0
	v_lshlrev_b32_e32 v0, 16, v102
	v_fmac_f32_e32 v32, v10, v0
	v_fmac_f32_e32 v56, v48, v0
	v_and_b32_e32 v0, 0xffff0000, v102
	v_fmac_f32_e32 v33, v11, v0
	v_fmac_f32_e32 v57, v49, v0
	v_lshlrev_b32_e32 v0, 16, v103
	v_fmac_f32_e32 v34, v12, v0
	v_fmac_f32_e32 v58, v50, v0
	v_and_b32_e32 v0, 0xffff0000, v103
	v_fmac_f32_e32 v35, v13, v0
	v_fmac_f32_e32 v59, v51, v0
	ds_read_b128 v[100:103], v178 offset:32768
	s_waitcnt lgkmcnt(4)
	v_lshlrev_b32_e32 v0, 16, v14
	v_fmac_f32_e32 v40, v92, v0
	v_fmac_f32_e32 v52, v36, v0
	v_and_b32_e32 v0, 0xffff0000, v14
	v_fmac_f32_e32 v41, v93, v0
	v_fmac_f32_e32 v53, v37, v0
	v_lshlrev_b32_e32 v0, 16, v15
	v_fmac_f32_e32 v42, v94, v0
	v_fmac_f32_e32 v54, v38, v0
	v_and_b32_e32 v0, 0xffff0000, v15
	v_fmac_f32_e32 v43, v95, v0
	v_fmac_f32_e32 v55, v39, v0
	v_lshlrev_b32_e32 v0, 16, v104
	v_fmac_f32_e32 v32, v96, v0
	v_fmac_f32_e32 v56, v10, v0
	v_and_b32_e32 v0, 0xffff0000, v104
	v_fmac_f32_e32 v33, v97, v0
	v_fmac_f32_e32 v57, v11, v0
	v_lshlrev_b32_e32 v0, 16, v105
	v_fmac_f32_e32 v34, v98, v0
	v_fmac_f32_e32 v58, v12, v0
	v_and_b32_e32 v0, 0xffff0000, v105
	v_fmac_f32_e32 v35, v99, v0
	v_fmac_f32_e32 v59, v13, v0
	s_waitcnt lgkmcnt(1)
	v_lshlrev_b32_e32 v0, 16, v60
	v_fmac_f32_e32 v40, v6, v0
	v_fmac_f32_e32 v52, v92, v0
	v_and_b32_e32 v0, 0xffff0000, v60
	v_fmac_f32_e32 v41, v7, v0
	v_fmac_f32_e32 v53, v93, v0
	v_lshlrev_b32_e32 v0, 16, v61
	v_fmac_f32_e32 v42, v8, v0
	v_fmac_f32_e32 v54, v94, v0
	v_and_b32_e32 v0, 0xffff0000, v61
	v_fmac_f32_e32 v43, v9, v0
	v_fmac_f32_e32 v55, v95, v0
	v_lshlrev_b32_e32 v0, 16, v62
	v_fmac_f32_e32 v32, v2, v0
	v_fmac_f32_e32 v56, v96, v0
	v_and_b32_e32 v0, 0xffff0000, v62
	v_fmac_f32_e32 v33, v3, v0
	v_fmac_f32_e32 v57, v97, v0
	v_lshlrev_b32_e32 v0, 16, v63
	v_fmac_f32_e32 v34, v4, v0
	v_fmac_f32_e32 v58, v98, v0
	v_and_b32_e32 v0, 0xffff0000, v63
	v_fmac_f32_e32 v35, v5, v0
	v_fmac_f32_e32 v59, v99, v0
	v_mul_f32_e32 v44, 0xbfb8aa3b, v40
	v_mul_f32_e32 v45, 0xbfb8aa3b, v41
	v_mul_f32_e32 v46, 0xbfb8aa3b, v42
	v_mul_f32_e32 v47, 0xbfb8aa3b, v43
	v_mul_f32_e32 v48, 0xbfb8aa3b, v32
	v_mul_f32_e32 v49, 0xbfb8aa3b, v33
	v_mul_f32_e32 v50, 0xbfb8aa3b, v34
	v_mul_f32_e32 v51, 0xbfb8aa3b, v35
	v_exp_f32_e32 v44, v44
	v_exp_f32_e32 v45, v45
	v_exp_f32_e32 v46, v46
	v_exp_f32_e32 v47, v47
	v_exp_f32_e32 v48, v48
	v_exp_f32_e32 v49, v49
	v_exp_f32_e32 v50, v50
	v_exp_f32_e32 v51, v51
	v_add_f32_e32 v44, 1.0, v44
	v_add_f32_e32 v45, 1.0, v45
	v_add_f32_e32 v46, 1.0, v46
	v_add_f32_e32 v47, 1.0, v47
	v_add_f32_e32 v48, 1.0, v48
	v_add_f32_e32 v49, 1.0, v49
	v_add_f32_e32 v50, 1.0, v50
	v_add_f32_e32 v51, 1.0, v51
	v_rcp_f32_e32 v44, v44
	v_rcp_f32_e32 v45, v45
	v_rcp_f32_e32 v46, v46
	v_rcp_f32_e32 v47, v47
	v_rcp_f32_e32 v48, v48
	v_rcp_f32_e32 v49, v49
	v_rcp_f32_e32 v50, v50
	v_rcp_f32_e32 v51, v51
	v_mul_f32_e32 v40, v40, v44
	v_mul_f32_e32 v41, v41, v45
	v_mul_f32_e32 v42, v42, v46
	v_mul_f32_e32 v43, v43, v47
	v_mul_f32_e32 v32, v32, v48
	v_mul_f32_e32 v33, v33, v49
	v_mul_f32_e32 v34, v34, v50
	v_mul_f32_e32 v35, v35, v51
	v_mul_f32_e32 v40, v40, v106
	v_mul_f32_e32 v41, v41, v106
	v_mul_f32_e32 v42, v42, v106
	v_mul_f32_e32 v43, v43, v106
	v_mul_f32_e32 v32, v32, v106
	v_mul_f32_e32 v33, v33, v106
	v_mul_f32_e32 v34, v34, v106
	v_mul_f32_e32 v35, v35, v106
	v_cvt_pk_bf16_f32 v44, v40, v41
	v_cvt_pk_bf16_f32 v45, v42, v43
	v_cvt_pk_bf16_f32 v46, v32, v33
	v_cvt_pk_bf16_f32 v47, v34, v35
	s_and_saveexec_b64 s[20:21], s[4:5]
	s_xor_b64 s[20:21], exec, s[20:21]
	s_cbranch_execz .Lcv_0_q
	ds_write_b128 v161, v[44:47] offset:9216
	ds_write_b128 v232, v[44:47] offset:18432
.Lcv_0_q:
	s_andn2_saveexec_b64 s[20:21], s[20:21]
	ds_write_b128 v161, v[44:47]
	s_or_b64 exec, exec, s[20:21]
	s_waitcnt lgkmcnt(3)
	v_lshlrev_b32_e32 v0, 16, v100
	v_fmac_f32_e32 v52, v6, v0
	v_and_b32_e32 v0, 0xffff0000, v100
	v_fmac_f32_e32 v53, v7, v0
	v_lshlrev_b32_e32 v0, 16, v101
	v_fmac_f32_e32 v54, v8, v0
	v_and_b32_e32 v0, 0xffff0000, v101
	v_fmac_f32_e32 v55, v9, v0
	v_lshlrev_b32_e32 v0, 16, v102
	v_fmac_f32_e32 v56, v2, v0
	v_and_b32_e32 v0, 0xffff0000, v102
	v_fmac_f32_e32 v57, v3, v0
	v_lshlrev_b32_e32 v0, 16, v103
	v_fmac_f32_e32 v58, v4, v0
	v_and_b32_e32 v0, 0xffff0000, v103
	v_fmac_f32_e32 v59, v5, v0
	v_mul_f32_e32 v92, 0xbfb8aa3b, v52
	v_mul_f32_e32 v93, 0xbfb8aa3b, v53
	v_mul_f32_e32 v94, 0xbfb8aa3b, v54
	v_mul_f32_e32 v95, 0xbfb8aa3b, v55
	v_mul_f32_e32 v96, 0xbfb8aa3b, v56
	v_mul_f32_e32 v97, 0xbfb8aa3b, v57
	v_mul_f32_e32 v98, 0xbfb8aa3b, v58
	v_mul_f32_e32 v99, 0xbfb8aa3b, v59
	v_exp_f32_e32 v92, v92
	v_exp_f32_e32 v93, v93
	v_exp_f32_e32 v94, v94
	v_exp_f32_e32 v95, v95
	v_exp_f32_e32 v96, v96
	v_exp_f32_e32 v97, v97
	v_exp_f32_e32 v98, v98
	v_exp_f32_e32 v99, v99
	v_add_f32_e32 v92, 1.0, v92
	v_add_f32_e32 v93, 1.0, v93
	v_add_f32_e32 v94, 1.0, v94
	v_add_f32_e32 v95, 1.0, v95
	v_add_f32_e32 v96, 1.0, v96
	v_add_f32_e32 v97, 1.0, v97
	v_add_f32_e32 v98, 1.0, v98
	v_add_f32_e32 v99, 1.0, v99
	v_rcp_f32_e32 v92, v92
	v_rcp_f32_e32 v93, v93
	v_rcp_f32_e32 v94, v94
	v_rcp_f32_e32 v95, v95
	v_rcp_f32_e32 v96, v96
	v_rcp_f32_e32 v97, v97
	v_rcp_f32_e32 v98, v98
	v_rcp_f32_e32 v99, v99
	v_mul_f32_e32 v52, v52, v92
	v_mul_f32_e32 v53, v53, v93
	v_mul_f32_e32 v54, v54, v94
	v_mul_f32_e32 v55, v55, v95
	v_mul_f32_e32 v56, v56, v96
	v_mul_f32_e32 v57, v57, v97
	v_mul_f32_e32 v58, v58, v98
	v_mul_f32_e32 v59, v59, v99
	v_mul_f32_e32 v52, v52, v106
	v_mul_f32_e32 v53, v53, v106
	v_mul_f32_e32 v54, v54, v106
	v_mul_f32_e32 v55, v55, v106
	v_mul_f32_e32 v56, v56, v106
	v_mul_f32_e32 v57, v57, v106
	v_mul_f32_e32 v58, v58, v106
	v_mul_f32_e32 v59, v59, v106
	v_cvt_pk_bf16_f32 v2, v52, v53
	v_cvt_pk_bf16_f32 v3, v54, v55
	v_cvt_pk_bf16_f32 v4, v56, v57
	v_cvt_pk_bf16_f32 v5, v58, v59
	s_and_saveexec_b64 s[20:21], s[4:5]
	s_xor_b64 s[20:21], exec, s[20:21]
	s_cbranch_execz .Lcv_1_q
	ds_write_b128 v179, v[2:5] offset:9216
	ds_write_b128 v233, v[2:5] offset:18432
